# attention inner loop: running row-max cross-lane steps via v_permlane16/32_swap instead of ds_bpermute round trips (4 sites)
# baseline (speedup 1.0000x reference)
; __device__ __forceinline__ void attn_phase(bf16_t* QKV, float* LSE, const float* rel_table, LAS unsigned char* lds, int bx, int Gd, int tid) {
;     ...
;             bf16x8 kf[2][2];
; #pragma unroll
;             for (int kt = 0; kt < 2; ++kt) { const int row = kbase + 16 * kt + fr;
; #pragma unroll
;                 for (int s2 = 0; s2 < 2; ++s2) kf[kt][s2] = *(const LAS bf16x8*)(lds + ATT_K + row * 128 + (((G + 4 * s2) ^ kswz(row)) * 16)); }
;             bf16x8 vf[4];
; #pragma unroll
;             for (int cc = 0; cc < 4; ++cc) {
;                 const int r0 = kbase + 4 * G + q4, r1 = r0 + 16;
;                 const s16x4 lo = __builtin_bit_cast(s16x4, __builtin_amdgcn_ds_read_tr16_b64_v4i16((LAS s16x4*)(lds + ATT_V + r0 * 128 + ((cc ^ ((r0 >> 1) & 3)) * 32) + 8 * p4)));
;                 const s16x4 hi = __builtin_bit_cast(s16x4, __builtin_amdgcn_ds_read_tr16_b64_v4i16((LAS s16x4*)(lds + ATT_V + r1 * 128 + ((cc ^ ((r1 >> 1) & 3)) * 32) + 8 * p4)));
;                 vf[cc] = (bf16x8){lo[0], lo[1], lo[2], lo[3], hi[0], hi[1], hi[2], hi[3]}; }
;             const bool edge = (c.qt == 0) && (kbase < 128);
; #pragma unroll
;             for (int qi = 0; qi < 2; ++qi) {
;                 f32x4 S[2];
; #pragma unroll
;                 for (int kt = 0; kt < 2; ++kt) { S[kt] = __builtin_amdgcn_mfma_f32_16x16x32_bf16(kf[kt][0], qf[qi][0], (f32x4){0.f, 0.f, 0.f, 0.f}, 0, 0, 0);
;                     S[kt] = __builtin_amdgcn_mfma_f32_16x16x32_bf16(kf[kt][1], qf[qi][1], S[kt], 0, 0, 0); }
;                 float mx = -1e30f;
; #pragma unroll
;                 for (int kt = 0; kt < 2; ++kt)
; #pragma unroll
;                     for (int i = 0; i < 4; ++i) { const int li = 159 + 16 * qi + fr - 4 * G - 32 * c5 - 16 * kt - i;
;                         float sv = S[kt][i] * c1 + lut[li];
;                         if (edge && (kbase + 16 * kt + 4 * G + i) < 128) sv = -1e30f;
;                         S[kt][i] = sv; mx = fmaxf(mx, sv); }
;                 mx = fmaxf(mx, __shfl_xor(mx, 16)); mx = fmaxf(mx, __shfl_xor(mx, 32));
;                 const float mnew = fmaxf(mrun[qi], mx), alpha = fast_exp2(mrun[qi] - mnew); mrun[qi] = mnew;
;                 float ps = 0.f;
; #pragma unroll
;                 for (int kt = 0; kt < 2; ++kt)
; #pragma unroll
;                     for (int i = 0; i < 4; ++i) { const float p = fast_exp2(S[kt][i] - mnew); S[kt][i] = p; ps += p; }
.LBB0_119:
	v_add_u32_e32 v112, 0, v173
	ds_read_b128 v[176:179], v112
	v_mov_b32_e32 v214, v163
	v_add_u32_e32 v113, 0, v171
	v_add_u32_e32 v114, 0, v168
	v_add_u32_e32 v163, 0, v167
	ds_read_b128 v[180:183], v113
	ds_read_b128 v[184:187], v112 offset:2048
	ds_read_b128 v[188:191], v113 offset:2048
	ds_read_b64_tr_b16 v[112:113], v114 offset:49152
	ds_read_b64_tr_b16 v[114:115], v114 offset:51200
	ds_read_b64_tr_b16 v[192:193], v163 offset:49152
	ds_read_b64_tr_b16 v[194:195], v163 offset:51200
	v_add_u32_e32 v163, 0, v166
	s_waitcnt lgkmcnt(7)
	v_mfma_f32_16x16x32_bf16 v[204:207], v[176:179], v[52:55], 0
	v_add_u32_e32 v216, 0, v164
	ds_read_b64_tr_b16 v[196:197], v163 offset:49152
	ds_read_b64_tr_b16 v[198:199], v163 offset:51200
	v_add_u32_e32 v163, 0, v165
	v_add_u32_e32 v218, 0x18278, v216
	v_mov_b32_e32 v212, v174
	ds_read_b64_tr_b16 v[200:201], v163 offset:49152
	ds_read_b64_tr_b16 v[202:203], v163 offset:51200
	ds_read2_b32 v[174:175], v218 offset1:1
	s_add_i32 s10, s7, s35
	s_waitcnt lgkmcnt(11)
	v_mfma_f32_16x16x32_bf16 v[204:207], v[180:183], v[48:51], v[204:207]
	s_cmpk_lt_i32 s10, 0x80
	s_cselect_b64 s[10:11], -1, 0
	v_add_u32_e32 v163, s35, v152
	s_and_b64 s[50:51], s[44:45], s[10:11]
	v_cmp_gt_i32_e32 vcc, s96, v163
	s_waitcnt lgkmcnt(0)
	s_nop 1
	v_fmamk_f32 v175, v204, 0x3e38aa3b, v175
	s_and_b64 vcc, s[50:51], vcc
	v_cndmask_b32_e32 v204, v175, v236, vcc
	v_add_u32_e32 v175, 1, v163
	v_cmp_gt_i32_e64 s[10:11], s96, v175
	v_fmac_f32_e32 v174, 0x3e38aa3b, v205
	s_and_b64 s[10:11], s[50:51], s[10:11]
	v_add_u32_e32 v220, 0x18270, v216
	v_cndmask_b32_e64 v205, v174, v236, s[10:11]
	ds_read2_b32 v[174:175], v220 offset1:1
	v_mfma_f32_16x16x32_bf16 v[208:211], v[184:187], v[52:55], 0
	v_add_u32_e32 v215, 16, v163
	v_cmp_gt_i32_e64 s[16:17], s96, v215
	s_and_b64 s[16:17], s[50:51], s[16:17]
	s_waitcnt lgkmcnt(0)
	v_fmamk_f32 v175, v206, 0x3e38aa3b, v175
	v_add_u32_e32 v206, 2, v163
	v_cmp_gt_i32_e64 s[12:13], s96, v206
	s_and_b64 s[12:13], s[50:51], s[12:13]
	v_fmac_f32_e32 v174, 0x3e38aa3b, v207
	v_cndmask_b32_e64 v206, v175, v236, s[12:13]
	v_add_u32_e32 v175, 3, v163
	v_cmp_gt_i32_e64 s[14:15], s96, v175
	s_and_b64 s[14:15], s[50:51], s[14:15]
	v_mfma_f32_16x16x32_bf16 v[208:211], v[188:191], v[48:51], v[208:211]
	v_cndmask_b32_e64 v207, v174, v236, s[14:15]
	v_add_u32_e32 v174, 0x18238, v216
	ds_read2_b32 v[174:175], v174 offset1:1
	v_max3_f32 v213, v204, s54, v205
	v_max3_f32 v213, v213, v206, v207
	v_mfma_f32_16x16x32_bf16 v[176:179], v[176:179], v[60:63], 0
	s_add_i32 s35, s35, 32
	s_waitcnt lgkmcnt(0)
	v_fmamk_f32 v175, v208, 0x3e38aa3b, v175
	v_cndmask_b32_e64 v208, v175, v236, s[16:17]
	v_add_u32_e32 v175, 17, v163
	v_cmp_gt_i32_e64 s[18:19], s96, v175
	v_fmac_f32_e32 v174, 0x3e38aa3b, v209
	s_and_b64 s[18:19], s[50:51], s[18:19]
	v_cndmask_b32_e64 v219, v174, v236, s[18:19]
	v_add_u32_e32 v174, 0x18230, v216
	ds_read2_b32 v[174:175], v174 offset1:1
	v_max3_f32 v209, v213, v208, v219
	v_mfma_f32_16x16x32_bf16 v[176:179], v[180:183], v[56:59], v[176:179]
	v_add_u32_e32 v173, 0x1000, v173
	v_add_u32_e32 v171, 0x1000, v171
	s_waitcnt lgkmcnt(0)
	v_fmamk_f32 v175, v210, 0x3e38aa3b, v175
	v_add_u32_e32 v210, 18, v163
	v_add_u32_e32 v163, 19, v163
	v_cmp_gt_i32_e64 s[20:21], s96, v210
	v_cmp_gt_i32_e64 s[22:23], s96, v163
	s_and_b64 s[20:21], s[50:51], s[20:21]
	v_fmac_f32_e32 v174, 0x3e38aa3b, v211
	s_and_b64 s[22:23], s[50:51], s[22:23]
	v_cndmask_b32_e64 v175, v175, v236, s[20:21]
	v_cndmask_b32_e64 v163, v174, v236, s[22:23]
	v_max3_f32 v174, v209, v175, v163
	v_mov_b32_e32 v209, v174
	s_nop 1
	v_permlane16_swap_b32_e32 v209, v174
	v_mfma_f32_16x16x32_bf16 v[180:183], v[184:187], v[60:63], 0
	v_add_u32_e32 v164, 0xffffff80, v164
	v_add_u32_e32 v168, 0x1000, v168
	v_add_u32_e32 v167, 0x1000, v167
	s_waitcnt lgkmcnt(0)
	v_max_f32_e32 v209, v209, v209
	v_max_f32_e32 v174, v174, v209
	v_mov_b32_e32 v209, v174
	s_nop 1
	v_permlane32_swap_b32_e32 v209, v174
	v_mfma_f32_16x16x32_bf16 v[180:183], v[188:191], v[56:59], v[180:183]
	v_add_u32_e32 v166, 0x1000, v166
	v_add_u32_e32 v165, 0x1000, v165
	s_cmpk_eq_i32 s35, 0xa0
	s_waitcnt lgkmcnt(0)
	v_max3_f32 v174, v212, v174, v209
	v_sub_f32_e32 v204, v204, v174
	v_exp_f32_e32 v209, v204
	v_sub_f32_e32 v204, v205, v174
	v_exp_f32_e32 v211, v204
	v_sub_f32_e32 v204, v206, v174
	v_exp_f32_e32 v213, v204
	v_sub_f32_e32 v204, v207, v174
	v_exp_f32_e32 v215, v204
	v_sub_f32_e32 v204, v208, v174
	v_sub_f32_e32 v163, v163, v174
	v_exp_f32_e32 v217, v204
	v_sub_f32_e32 v204, v219, v174
	v_sub_f32_e32 v175, v175, v174
	v_exp_f32_e32 v241, v163
	v_add_u32_e32 v163, 0x182b8, v216
	v_exp_f32_e32 v219, v204
	v_exp_f32_e32 v221, v175
	v_cvt_pk_bf16_f32 v204, v209, v211
	v_cvt_pk_bf16_f32 v205, v213, v215
	v_cvt_pk_bf16_f32 v206, v217, v219
	v_cvt_pk_bf16_f32 v207, v221, v241
	ds_read2_b32 v[184:185], v163 offset1:1
	v_sub_f32_e32 v210, v212, v174
	v_exp_f32_e32 v242, v210
	s_waitcnt lgkmcnt(0)
	v_fmamk_f32 v163, v176, 0x3e38aa3b, v185
	v_add_u32_e32 v176, 0x182b0, v216
	v_fmac_f32_e32 v184, 0x3e38aa3b, v177
	ds_read2_b32 v[176:177], v176 offset1:1
	v_cndmask_b32_e32 v175, v163, v236, vcc
	v_cndmask_b32_e64 v184, v184, v236, s[10:11]
	v_max3_f32 v163, v175, s54, v184
	v_pk_mul_f32 v[110:111], v[110:111], v[242:243] op_sel_hi:[1,0]
	s_waitcnt lgkmcnt(0)
	v_fmamk_f32 v177, v178, 0x3e38aa3b, v177
	v_fmac_f32_e32 v176, 0x3e38aa3b, v179
	v_cndmask_b32_e64 v178, v177, v236, s[12:13]
	v_cndmask_b32_e64 v179, v176, v236, s[14:15]
	ds_read2_b32 v[176:177], v218 offset1:1
	v_max3_f32 v163, v163, v178, v179
	v_pk_mul_f32 v[108:109], v[108:109], v[242:243] op_sel_hi:[1,0]
	v_pk_mul_f32 v[106:107], v[106:107], v[242:243] op_sel_hi:[1,0]
	v_pk_mul_f32 v[104:105], v[104:105], v[242:243] op_sel_hi:[1,0]
	s_waitcnt lgkmcnt(0)
; __device__ __forceinline__ unsigned cvt_pk_bf16(float lo, float hi) { unsigned r; asm volatile("v_cvt_pk_bf16_f32 %0, %1, %2" : "=v"(r) : "v"(lo), "v"(hi)); return r; }
; __device__ __forceinline__ float fast_exp2(float x) { return __builtin_amdgcn_exp2f(x); }
; __device__ __forceinline__ void attn_phase(bf16_t* QKV, float* LSE, const float* rel_table, LAS unsigned char* lds, int bx, int Gd, int tid) {
;     ...
;                 mx = fmaxf(mx, __shfl_xor(mx, 16)); mx = fmaxf(mx, __shfl_xor(mx, 32));
;                 const float mnew = fmaxf(mrun[qi], mx), alpha = fast_exp2(mrun[qi] - mnew); mrun[qi] = mnew;
;                 float ps = 0.f;
; #pragma unroll
;                 for (int kt = 0; kt < 2; ++kt)
; #pragma unroll
;                     for (int i = 0; i < 4; ++i) { const float p = fast_exp2(S[kt][i] - mnew); S[kt][i] = p; ps += p; }
;                 lsum[qi] = lsum[qi] * alpha + ps;
;                 u32x4 pw; pw.x = cvt_pk_bf16(S[0][0], S[0][1]); pw.y = cvt_pk_bf16(S[0][2], S[0][3]); pw.z = cvt_pk_bf16(S[1][0], S[1][1]); pw.w = cvt_pk_bf16(S[1][2], S[1][3]);
;                 const bf16x8 pf = __builtin_bit_cast(bf16x8, pw);
; #pragma unroll
;                 for (int cc = 0; cc < 4; ++cc) { O[qi][cc] = O[qi][cc] * alpha; O[qi][cc] = __builtin_amdgcn_mfma_f32_16x16x32_bf16(vf[cc], pf, O[qi][cc], 0, 0, 0); }
;             }
;         }
; #pragma unroll
;         for (int qi = 0; qi < 2; ++qi) {
;             float l = lsum[qi]; l += __shfl_xor(l, 16); l += __shfl_xor(l, 32);
;             const float inv = 1.0f / l;
;             const size_t tok = c.tok0 + (size_t)(c.N0 + 32 * w + 16 * qi + fr) * c.d;
;             bf16_t* op = QKV + tok * NQKV + c.qcol + 4 * G;
; #pragma unroll
;             for (int cc = 0; cc < 4; ++cc) { u32x2 o; o.x = cvt_pk_bf16(O[qi][cc][0] * inv, O[qi][cc][1] * inv); o.y = cvt_pk_bf16(O[qi][cc][2] * inv, O[qi][cc][3] * inv); *(u32x2*)(op + 16 * cc) = o; }
;             if (G == 0) LSE[(tok * 3 + c.g) * 8 + c.h] = mrun[qi] + __log2f(l);
	v_fmamk_f32 v177, v180, 0x3e38aa3b, v177
	v_fmac_f32_e32 v176, 0x3e38aa3b, v181
	v_cndmask_b32_e64 v180, v177, v236, s[16:17]
	v_cndmask_b32_e64 v181, v176, v236, s[18:19]
	ds_read2_b32 v[176:177], v220 offset1:1
	v_max3_f32 v163, v163, v180, v181
	v_pk_mul_f32 v[102:103], v[102:103], v[242:243] op_sel_hi:[1,0]
	v_pk_mul_f32 v[100:101], v[100:101], v[242:243] op_sel_hi:[1,0]
	v_pk_mul_f32 v[98:99], v[98:99], v[242:243] op_sel_hi:[1,0]
	s_waitcnt lgkmcnt(0)
	v_fmamk_f32 v177, v182, 0x3e38aa3b, v177
	v_fmac_f32_e32 v176, 0x3e38aa3b, v183
	v_cndmask_b32_e64 v177, v177, v236, s[20:21]
	v_cndmask_b32_e64 v176, v176, v236, s[22:23]
	v_max3_f32 v163, v163, v177, v176
	v_mov_b32_e32 v182, v163
	s_nop 1
	v_permlane16_swap_b32_e32 v182, v163
	v_pk_mul_f32 v[96:97], v[96:97], v[242:243] op_sel_hi:[1,0]
	v_mfma_f32_16x16x32_bf16 v[108:111], v[112:115], v[204:207], v[108:111]
	s_waitcnt lgkmcnt(0)
	v_max_f32_e32 v182, v182, v182
	v_max_f32_e32 v163, v163, v182
	v_mov_b32_e32 v182, v163
	s_nop 1
	v_permlane32_swap_b32_e32 v182, v163
	v_mfma_f32_16x16x32_bf16 v[104:107], v[192:195], v[204:207], v[104:107]
	s_waitcnt lgkmcnt(0)
	v_max3_f32 v163, v214, v163, v182
	v_sub_f32_e32 v175, v175, v163
	v_exp_f32_e32 v208, v175
	v_sub_f32_e32 v175, v184, v163
	v_exp_f32_e32 v210, v175
	v_sub_f32_e32 v175, v178, v163
	v_exp_f32_e32 v212, v175
	v_sub_f32_e32 v175, v179, v163
	v_sub_f32_e32 v182, v214, v163
	v_exp_f32_e32 v214, v175
	v_sub_f32_e32 v175, v180, v163
	v_exp_f32_e32 v216, v175
	v_sub_f32_e32 v175, v181, v163
	v_exp_f32_e32 v218, v175
	v_sub_f32_e32 v175, v177, v163
	v_exp_f32_e32 v220, v175
	v_sub_f32_e32 v175, v176, v163
	v_pk_add_f32 v[176:177], v[208:209], 0 op_sel_hi:[1,0]
	v_exp_f32_e32 v240, v175
	v_pk_add_f32 v[176:177], v[210:211], v[176:177]
	v_exp_f32_e32 v180, v182
	v_pk_add_f32 v[176:177], v[212:213], v[176:177]
	v_mov_b32_e32 v181, v242
	v_pk_add_f32 v[176:177], v[214:215], v[176:177]
	v_pk_mul_f32 v[94:95], v[94:95], v[180:181] op_sel_hi:[1,0]
	v_pk_add_f32 v[176:177], v[216:217], v[176:177]
	v_pk_mul_f32 v[92:93], v[92:93], v[180:181] op_sel_hi:[1,0]
	v_pk_add_f32 v[176:177], v[218:219], v[176:177]
	v_pk_mul_f32 v[90:91], v[90:91], v[180:181] op_sel_hi:[1,0]
	v_pk_add_f32 v[176:177], v[220:221], v[176:177]
	v_pk_mul_f32 v[88:89], v[88:89], v[180:181] op_sel_hi:[1,0]
	v_pk_add_f32 v[176:177], v[240:241], v[176:177]
	v_pk_mul_f32 v[86:87], v[86:87], v[180:181] op_sel_hi:[1,0]
	v_pk_mul_f32 v[84:85], v[84:85], v[180:181] op_sel_hi:[1,0]
	v_pk_mul_f32 v[82:83], v[82:83], v[180:181] op_sel_hi:[1,0]
	v_pk_mul_f32 v[80:81], v[80:81], v[180:181] op_sel_hi:[1,0]
	v_mfma_f32_16x16x32_bf16 v[100:103], v[196:199], v[204:207], v[100:103]
	v_fma_f32 v124, v124, v180, v176
	v_fma_f32 v125, v125, v181, v177
	v_cvt_pk_bf16_f32 v176, v208, v210
	v_cvt_pk_bf16_f32 v177, v212, v214
	v_mfma_f32_16x16x32_bf16 v[96:99], v[200:203], v[204:207], v[96:99]
	v_cvt_pk_bf16_f32 v178, v216, v218
	v_cvt_pk_bf16_f32 v179, v220, v240
	s_nop 0
	v_mfma_f32_16x16x32_bf16 v[92:95], v[112:115], v[176:179], v[92:95]
	v_mfma_f32_16x16x32_bf16 v[88:91], v[192:195], v[176:179], v[88:91]
	v_mfma_f32_16x16x32_bf16 v[84:87], v[196:199], v[176:179], v[84:87]
	v_mfma_f32_16x16x32_bf16 v[80:83], v[200:203], v[176:179], v[80:83]
	s_cbranch_scc0 .LBB0_119
	ds_bpermute_b32 v50, v123, v125
	v_add_u32_e32 v54, s29, v142
	s_ashr_i32 s35, s34, 31
	v_lshl_add_u64 v[48:49], s[34:35], 1, v[118:119]
	s_ashr_i32 s29, s28, 31
	s_waitcnt lgkmcnt(0)
	v_add_f32_e32 v50, v125, v50
	ds_bpermute_b32 v51, v121, v50
	s_lshl_b64 s[10:11], s[94:95], 2
	s_add_u32 s10, s26, s10
	s_addc_u32 s11, s27, s11
	s_waitcnt lgkmcnt(0)
	v_add_f32_e32 v56, v50, v51
	v_div_scale_f32 v50, s[12:13], v56, v56, 1.0
	v_rcp_f32_e32 v51, v50
	s_nop 0
	v_fma_f32 v52, -v50, v51, 1.0
	v_fmac_f32_e32 v51, v52, v51
	v_div_scale_f32 v52, vcc, 1.0, v56, 1.0
	v_mul_f32_e32 v53, v52, v51
	v_fma_f32 v55, -v50, v53, v52
	v_fmac_f32_e32 v53, v55, v51
	v_fma_f32 v50, -v50, v53, v52
	v_div_fmas_f32 v50, v50, v51, v53
	v_div_fixup_f32 v57, v50, v56, 1.0
	v_mov_b64_e32 v[50:51], s[30:31]
	v_mad_u64_u32 v[52:53], s[12:13], v54, s1, v[50:51]
	v_ashrrev_i32_e32 v55, 31, v54
	v_mov_b32_e32 v50, v53
	v_mad_u64_u32 v[58:59], s[12:13], v52, s53, v[48:49]
	v_mad_u64_u32 v[50:51], s[12:13], v55, s1, v[50:51]
	v_mov_b32_e32 v60, v59
	v_mad_u64_u32 v[60:61], s[12:13], v50, s53, v[60:61]
	v_mul_f32_e32 v51, v108, v57
	v_mul_f32_e32 v53, v109, v57
	v_mov_b32_e32 v59, v60
	v_cvt_pk_bf16_f32 v60, v51, v53
	v_mul_f32_e32 v51, v110, v57
	v_mul_f32_e32 v53, v111, v57
	v_cvt_pk_bf16_f32 v61, v51, v53
	v_mul_f32_e32 v51, v104, v57
	v_mul_f32_e32 v53, v105, v57
	global_store_dwordx2 v[58:59], v[60:61], off
	v_cvt_pk_bf16_f32 v60, v51, v53
	v_mul_f32_e32 v51, v106, v57
	v_mul_f32_e32 v53, v107, v57
	v_cvt_pk_bf16_f32 v61, v51, v53
	v_mul_f32_e32 v51, v100, v57
	v_mul_f32_e32 v53, v101, v57
	global_store_dwordx2 v[58:59], v[60:61], off offset:32
	v_cvt_pk_bf16_f32 v60, v51, v53
	v_mul_f32_e32 v51, v102, v57
	v_mul_f32_e32 v53, v103, v57
	v_cvt_pk_bf16_f32 v61, v51, v53
	v_mul_f32_e32 v51, v96, v57
	v_mul_f32_e32 v53, v97, v57
	global_store_dwordx2 v[58:59], v[60:61], off offset:64
	v_cvt_pk_bf16_f32 v60, v51, v53
	v_mul_f32_e32 v51, v98, v57
	v_mul_f32_e32 v53, v99, v57
	v_cvt_pk_bf16_f32 v61, v51, v53
	global_store_dwordx2 v[58:59], v[60:61], off offset:96
	s_and_saveexec_b64 s[12:13], s[8:9]
	s_cbranch_execz .LBB0_122
	v_log_f32_e32 v51, v56
	v_mad_u64_u32 v[52:53], s[14:15], v52, 3, s[28:29]
	v_mov_b32_e32 v56, v53
	v_add_f32_e32 v57, v174, v51
	v_mad_u64_u32 v[50:51], s[14:15], v50, 3, v[56:57]
	v_mov_b32_e32 v53, v50
	v_lshlrev_b64 v[50:51], 5, v[52:53]
	v_lshl_add_u64 v[50:51], s[10:11], 0, v[50:51]
	global_store_dword v[50:51], v57, off
